# P10: the FfnUp epilogue's 8 row-statistic loads issued before the unit's K-loop (the epilogue no longer queues behind the next unit's prefetch DMAs)
# baseline (speedup 1.0000x reference)
; template <class Epi, class Sched, bool ALIGN_EPI = false, bool SP2 = false>
; __device__ __forceinline__ void gemm_phase(PG8_LAS unsigned char* lds, const Gemm g, const Sched& S, const Epi& E, const int wid) {
;     ...
; #pragma unroll
;         for (int a = 0; a < 2; ++a)
; #pragma unroll
;             for (int b = 0; b < 2; ++b)
; #pragma unroll
;                 for (int m = 0; m < 4; ++m)
; #pragma unroll
;                     for (int n = 0; n < 2; ++n) acc[a][b][m][n] = (f32x4){0.f, 0.f, 0.f, 0.f};
;     DI void operator()(f4 (&acc)[2][2][4][2], const Unit& u, int wr, int wc, int fr, int fq) const {
;     ...
;         for (int ai = 0; ai < 2; ++ai)
; #pragma unroll
;             for (int m = 0; m < 4; ++m) rr[ai][m] = ss[row0 + ai * HALF + m * 16];
.LBB0_2809:
	s_ashr_i32 s23, s22, 31
	s_lshl_b64 s[24:25], s[22:23], 21
	s_add_u32 s24, s30, s24
	s_addc_u32 s25, s31, s25
	s_and_b64 s[26:27], s[4:5], exec
	s_cselect_b32 s23, s25, s3
	s_cselect_b32 s53, s24, s2
	s_ashr_i32 s21, s20, 31
	s_lshl_b64 s[26:27], s[20:21], 21
	s_add_u32 s26, s35, s26
	s_addc_u32 s27, s41, s27
	s_and_b64 s[28:29], s[4:5], exec
	s_cselect_b32 s21, s27, s7
	s_cselect_b32 s54, s26, s6
	s_add_u32 s2, s2, 0x100080
	s_addc_u32 s3, s3, 0
	s_add_u32 s55, s6, 0x100
	v_mov_b32_e32 v0, 0
	s_addc_u32 s56, s7, 0
	s_mov_b32 s57, -2
	v_mov_b32_e32 v1, v0
	v_mov_b32_e32 v2, v0
	v_mov_b32_e32 v3, v0
	v_mov_b32_e32 v8, v0
	v_mov_b32_e32 v9, v0
	v_mov_b32_e32 v10, v0
	v_mov_b32_e32 v11, v0
	v_mov_b32_e32 v16, v0
	v_mov_b32_e32 v17, v0
	v_mov_b32_e32 v18, v0
	v_mov_b32_e32 v19, v0
	v_mov_b32_e32 v24, v0
	v_mov_b32_e32 v25, v0
	v_mov_b32_e32 v26, v0
	v_mov_b32_e32 v27, v0
	v_mov_b32_e32 v32, v0
	v_mov_b32_e32 v33, v0
	v_mov_b32_e32 v34, v0
	v_mov_b32_e32 v35, v0
	v_mov_b32_e32 v40, v0
	v_mov_b32_e32 v41, v0
	v_mov_b32_e32 v42, v0
	v_mov_b32_e32 v43, v0
	v_mov_b32_e32 v48, v0
	v_mov_b32_e32 v49, v0
	v_mov_b32_e32 v50, v0
	v_mov_b32_e32 v51, v0
	v_mov_b32_e32 v56, v0
	v_mov_b32_e32 v57, v0
	v_mov_b32_e32 v58, v0
	v_mov_b32_e32 v59, v0
	v_mov_b32_e32 v4, v0
	v_mov_b32_e32 v5, v0
	v_mov_b32_e32 v6, v0
	v_mov_b32_e32 v7, v0
	v_mov_b32_e32 v12, v0
	v_mov_b32_e32 v13, v0
	v_mov_b32_e32 v14, v0
	v_mov_b32_e32 v15, v0
	v_mov_b32_e32 v20, v0
	v_mov_b32_e32 v21, v0
	v_mov_b32_e32 v22, v0
	v_mov_b32_e32 v23, v0
	v_mov_b32_e32 v28, v0
	v_mov_b32_e32 v29, v0
	v_mov_b32_e32 v30, v0
	v_mov_b32_e32 v31, v0
	v_mov_b32_e32 v36, v0
	v_mov_b32_e32 v37, v0
	v_mov_b32_e32 v38, v0
	v_mov_b32_e32 v39, v0
	v_mov_b32_e32 v44, v0
	v_mov_b32_e32 v45, v0
	v_mov_b32_e32 v46, v0
	v_mov_b32_e32 v47, v0
	v_mov_b32_e32 v52, v0
	v_mov_b32_e32 v53, v0
	v_mov_b32_e32 v54, v0
	v_mov_b32_e32 v55, v0
	v_mov_b32_e32 v60, v0
	v_mov_b32_e32 v61, v0
	v_mov_b32_e32 v62, v0
	v_mov_b32_e32 v63, v0
	v_mov_b32_e32 v64, v0
	v_mov_b32_e32 v65, v0
	v_mov_b32_e32 v66, v0
	v_mov_b32_e32 v67, v0
	v_mov_b32_e32 v72, v0
	v_mov_b32_e32 v73, v0
	v_mov_b32_e32 v74, v0
	v_mov_b32_e32 v75, v0
	v_mov_b32_e32 v80, v0
	v_mov_b32_e32 v81, v0
	v_mov_b32_e32 v82, v0
	v_mov_b32_e32 v83, v0
	v_mov_b32_e32 v88, v0
	v_mov_b32_e32 v89, v0
	v_mov_b32_e32 v90, v0
	v_mov_b32_e32 v91, v0
	v_mov_b32_e32 v96, v0
	v_mov_b32_e32 v97, v0
	v_mov_b32_e32 v98, v0
	v_mov_b32_e32 v99, v0
	v_mov_b32_e32 v104, v0
	v_mov_b32_e32 v105, v0
	v_mov_b32_e32 v106, v0
	v_mov_b32_e32 v107, v0
	v_mov_b32_e32 v112, v0
	v_mov_b32_e32 v113, v0
	v_mov_b32_e32 v114, v0
	v_mov_b32_e32 v115, v0
	v_mov_b32_e32 v120, v0
	v_mov_b32_e32 v121, v0
	v_mov_b32_e32 v122, v0
	v_mov_b32_e32 v123, v0
	v_mov_b32_e32 v68, v0
	v_mov_b32_e32 v69, v0
	v_mov_b32_e32 v70, v0
	v_mov_b32_e32 v71, v0
	v_mov_b32_e32 v76, v0
	v_mov_b32_e32 v77, v0
	v_mov_b32_e32 v78, v0
	v_mov_b32_e32 v79, v0
	v_mov_b32_e32 v84, v0
	v_mov_b32_e32 v85, v0
	v_mov_b32_e32 v86, v0
	v_mov_b32_e32 v87, v0
	v_mov_b32_e32 v92, v0
	v_mov_b32_e32 v93, v0
	v_mov_b32_e32 v94, v0
	v_mov_b32_e32 v95, v0
	v_mov_b32_e32 v100, v0
	v_mov_b32_e32 v101, v0
	v_mov_b32_e32 v102, v0
	v_mov_b32_e32 v103, v0
	v_mov_b32_e32 v108, v0
	v_mov_b32_e32 v109, v0
	v_mov_b32_e32 v110, v0
	v_mov_b32_e32 v111, v0
	v_mov_b32_e32 v116, v0
	v_mov_b32_e32 v117, v0
	v_mov_b32_e32 v118, v0
	v_mov_b32_e32 v119, v0
	v_mov_b32_e32 v124, v0
	v_mov_b32_e32 v125, v0
	v_mov_b32_e32 v126, v0
	v_mov_b32_e32 v127, v0
	s_lshl_b32 s98, s0, 8
	s_add_i32 s98, s98, s36
	v_mbcnt_lo_u32_b32 v232, -1, 0
	v_mbcnt_hi_u32_b32 v232, -1, v232
	v_and_or_b32 v232, v232, 15, s98
	v_ashrrev_i32_e32 v233, 31, v232
	v_lshl_add_u64 v[232:233], v[232:233], 2, s[10:11]
	global_load_dword v224, v[232:233], off
	global_load_dword v225, v[232:233], off offset:64
	global_load_dword v226, v[232:233], off offset:128
	global_load_dword v227, v[232:233], off offset:192
	global_load_dword v228, v[232:233], off offset:512
	global_load_dword v229, v[232:233], off offset:576
	global_load_dword v230, v[232:233], off offset:640
	global_load_dword v231, v[232:233], off offset:704

; DI float sigmoidf_(float z) { return 1.0f / (1.0f + __expf(-z)); }
; DI v4u pack8(const f4& a, const f4& b) { v4u w; w.x = cvt_pk_bf16(a[0], a[1]); w.y = cvt_pk_bf16(a[2], a[3]); w.z = cvt_pk_bf16(b[0], b[1]); w.w = cvt_pk_bf16(b[2], b[3]); return w; }
;     DI void operator()(f4 (&acc)[2][2][4][2], const Unit& u, int wr, int wc, int fr, int fq) const {
;     ...
; #pragma unroll
;         for (int ai = 0; ai < 2; ++ai)
; #pragma unroll
;             for (int m = 0; m < 4; ++m) { const int row = row0 + ai * HALF + m * 16; const float r = __builtin_amdgcn_rsqf(rr[ai][m] * (1.0f / D) + RMS_EPS);
;                 f4 o0, o1;
; #pragma unroll
;                 for (int e = 0; e < 4; ++e) { const float a0 = acc[ai][0][m][0][e] * r, a1 = acc[ai][0][m][1][e] * r;
;                     o0[e] = a0 * sigmoidf_(a0) * (acc[ai][1][m][0][e] * r); o1[e] = a1 * sigmoidf_(a1) * (acc[ai][1][m][1][e] * r); }
;                 *(v4u*)(uout + (size_t)row * DFF + col0) = pack8(o0, o1); }
.LBB0_2813:
	s_lshl_b32 s0, s0, 8
	s_add_i32 s0, s0, s36
	v_mbcnt_lo_u32_b32 v144, -1, 0
	v_mbcnt_hi_u32_b32 v144, -1, v144
	v_and_or_b32 v148, v144, 15, s0
	v_ashrrev_i32_e32 v149, 31, v148
	s_lshl_b32 s0, s1, 7
	s_or_b32 s0, s0, s37
	v_ashrrev_i32_e32 v145, 1, v144
	v_and_b32_e32 v145, -8, v145
	v_add_u32_e32 v164, s0, v145
	v_ashrrev_i32_e32 v165, 31, v164
	v_lshlrev_b64 v[164:165], 1, v[164:165]
	v_lshl_add_u64 v[164:165], v[164:165], 0, s[14:15]
	v_fmamk_f32 v166, v224, 0x39800000, v154
	v_rsq_f32_e32 v167, v166
	v_pk_mul_f32 v[120:121], v[124:125], v[120:121]
	v_pk_mul_f32 v[122:123], v[126:127], v[122:123]
	v_pk_mul_f32 v[112:113], v[116:117], v[112:113]
	v_pk_mul_f32 v[114:115], v[118:119], v[114:115]
	v_mul_f32_e32 v168, 0xbfb8aa3b, v167
	v_mov_b32_e32 v149, v148
	v_pk_mul_f32 v[124:125], v[124:125], v[168:169] op_sel_hi:[1,0]
	v_pk_mul_f32 v[126:127], v[126:127], v[168:169] op_sel_hi:[1,0]
	v_pk_mul_f32 v[116:117], v[116:117], v[168:169] op_sel_hi:[1,0]
	v_pk_mul_f32 v[118:119], v[118:119], v[168:169] op_sel_hi:[1,0]
	v_exp_f32_e32 v124, v124
	v_exp_f32_e32 v125, v125
	v_exp_f32_e32 v126, v126
	v_exp_f32_e32 v127, v127
	v_exp_f32_e32 v116, v116
	v_exp_f32_e32 v117, v117
	v_exp_f32_e32 v118, v118
	v_exp_f32_e32 v119, v119
	v_mad_i64_i32 v[170:171], s[0:1], v149, s52, v[164:165]
	v_pk_fma_f32 v[124:125], v[124:125], v[166:167], v[166:167] op_sel_hi:[1,0,0]
	v_pk_fma_f32 v[126:127], v[126:127], v[166:167], v[166:167] op_sel_hi:[1,0,0]
	v_pk_fma_f32 v[116:117], v[116:117], v[166:167], v[166:167] op_sel_hi:[1,0,0]
	v_pk_fma_f32 v[118:119], v[118:119], v[166:167], v[166:167] op_sel_hi:[1,0,0]
	v_rcp_f32_e32 v124, v124
	v_rcp_f32_e32 v125, v125
	v_rcp_f32_e32 v126, v126
	v_rcp_f32_e32 v127, v127
	v_rcp_f32_e32 v116, v116
	v_rcp_f32_e32 v117, v117
	v_rcp_f32_e32 v118, v118
	v_rcp_f32_e32 v119, v119
	s_nop 0
	v_pk_mul_f32 v[120:121], v[120:121], v[124:125]
	v_pk_mul_f32 v[122:123], v[122:123], v[126:127]
	v_pk_mul_f32 v[112:113], v[112:113], v[116:117]
	v_pk_mul_f32 v[114:115], v[114:115], v[118:119]
	v_cvt_pk_bf16_f32 v124, v120, v121
	v_cvt_pk_bf16_f32 v125, v122, v123
	v_cvt_pk_bf16_f32 v126, v112, v113
	v_cvt_pk_bf16_f32 v127, v114, v115
	global_store_dwordx4 v[170:171], v[124:127], off
	v_fmamk_f32 v166, v225, 0x39800000, v154
	v_rsq_f32_e32 v167, v166
	v_pk_mul_f32 v[104:105], v[108:109], v[104:105]
	v_pk_mul_f32 v[106:107], v[110:111], v[106:107]
	v_pk_mul_f32 v[96:97], v[100:101], v[96:97]
	v_pk_mul_f32 v[98:99], v[102:103], v[98:99]
	v_mul_f32_e32 v168, 0xbfb8aa3b, v167
	v_add_u32_e32 v149, 0x10, v148
	v_pk_mul_f32 v[108:109], v[108:109], v[168:169] op_sel_hi:[1,0]
	v_pk_mul_f32 v[110:111], v[110:111], v[168:169] op_sel_hi:[1,0]
	v_pk_mul_f32 v[100:101], v[100:101], v[168:169] op_sel_hi:[1,0]
	v_pk_mul_f32 v[102:103], v[102:103], v[168:169] op_sel_hi:[1,0]
	v_exp_f32_e32 v108, v108
	v_exp_f32_e32 v109, v109
	v_exp_f32_e32 v110, v110
	v_exp_f32_e32 v111, v111
	v_exp_f32_e32 v100, v100
	v_exp_f32_e32 v101, v101
	v_exp_f32_e32 v102, v102
	v_exp_f32_e32 v103, v103
	v_mad_i64_i32 v[170:171], s[0:1], v149, s52, v[164:165]
	v_pk_fma_f32 v[108:109], v[108:109], v[166:167], v[166:167] op_sel_hi:[1,0,0]
	v_pk_fma_f32 v[110:111], v[110:111], v[166:167], v[166:167] op_sel_hi:[1,0,0]
	v_pk_fma_f32 v[100:101], v[100:101], v[166:167], v[166:167] op_sel_hi:[1,0,0]
	v_pk_fma_f32 v[102:103], v[102:103], v[166:167], v[166:167] op_sel_hi:[1,0,0]
	v_rcp_f32_e32 v108, v108
	v_rcp_f32_e32 v109, v109
	v_rcp_f32_e32 v110, v110
	v_rcp_f32_e32 v111, v111
	v_rcp_f32_e32 v100, v100
	v_rcp_f32_e32 v101, v101
	v_rcp_f32_e32 v102, v102
	v_rcp_f32_e32 v103, v103
	s_nop 0
	v_pk_mul_f32 v[104:105], v[104:105], v[108:109]
	v_pk_mul_f32 v[106:107], v[106:107], v[110:111]
	v_pk_mul_f32 v[96:97], v[96:97], v[100:101]
	v_pk_mul_f32 v[98:99], v[98:99], v[102:103]
	v_cvt_pk_bf16_f32 v108, v104, v105
	v_cvt_pk_bf16_f32 v109, v106, v107
	v_cvt_pk_bf16_f32 v110, v96, v97
	v_cvt_pk_bf16_f32 v111, v98, v99
	global_store_dwordx4 v[170:171], v[108:111], off
	v_fmamk_f32 v166, v226, 0x39800000, v154
	v_rsq_f32_e32 v167, v166
	v_pk_mul_f32 v[88:89], v[92:93], v[88:89]
	v_pk_mul_f32 v[90:91], v[94:95], v[90:91]
	v_pk_mul_f32 v[80:81], v[84:85], v[80:81]
	v_pk_mul_f32 v[82:83], v[86:87], v[82:83]
	v_mul_f32_e32 v168, 0xbfb8aa3b, v167
	v_add_u32_e32 v149, 0x20, v148
	v_pk_mul_f32 v[92:93], v[92:93], v[168:169] op_sel_hi:[1,0]
	v_pk_mul_f32 v[94:95], v[94:95], v[168:169] op_sel_hi:[1,0]
	v_pk_mul_f32 v[84:85], v[84:85], v[168:169] op_sel_hi:[1,0]
	v_pk_mul_f32 v[86:87], v[86:87], v[168:169] op_sel_hi:[1,0]
	v_exp_f32_e32 v92, v92
	v_exp_f32_e32 v93, v93
	v_exp_f32_e32 v94, v94
	v_exp_f32_e32 v95, v95
	v_exp_f32_e32 v84, v84
	v_exp_f32_e32 v85, v85
	v_exp_f32_e32 v86, v86
	v_exp_f32_e32 v87, v87
	v_mad_i64_i32 v[170:171], s[0:1], v149, s52, v[164:165]
	v_pk_fma_f32 v[92:93], v[92:93], v[166:167], v[166:167] op_sel_hi:[1,0,0]
	v_pk_fma_f32 v[94:95], v[94:95], v[166:167], v[166:167] op_sel_hi:[1,0,0]
	v_pk_fma_f32 v[84:85], v[84:85], v[166:167], v[166:167] op_sel_hi:[1,0,0]
	v_pk_fma_f32 v[86:87], v[86:87], v[166:167], v[166:167] op_sel_hi:[1,0,0]
	v_rcp_f32_e32 v92, v92
	v_rcp_f32_e32 v93, v93
	v_rcp_f32_e32 v94, v94
	v_rcp_f32_e32 v95, v95
	v_rcp_f32_e32 v84, v84
	v_rcp_f32_e32 v85, v85
	v_rcp_f32_e32 v86, v86
	v_rcp_f32_e32 v87, v87
	s_nop 0
	v_pk_mul_f32 v[88:89], v[88:89], v[92:93]
	v_pk_mul_f32 v[90:91], v[90:91], v[94:95]
	v_pk_mul_f32 v[80:81], v[80:81], v[84:85]
	v_pk_mul_f32 v[82:83], v[82:83], v[86:87]
	v_cvt_pk_bf16_f32 v92, v88, v89
	v_cvt_pk_bf16_f32 v93, v90, v91
	v_cvt_pk_bf16_f32 v94, v80, v81
	v_cvt_pk_bf16_f32 v95, v82, v83
	global_store_dwordx4 v[170:171], v[92:95], off
; DI float sigmoidf_(float z) { return 1.0f / (1.0f + __expf(-z)); }
; DI v4u pack8(const f4& a, const f4& b) { v4u w; w.x = cvt_pk_bf16(a[0], a[1]); w.y = cvt_pk_bf16(a[2], a[3]); w.z = cvt_pk_bf16(b[0], b[1]); w.w = cvt_pk_bf16(b[2], b[3]); return w; }
;     DI void operator()(f4 (&acc)[2][2][4][2], const Unit& u, int wr, int wc, int fr, int fq) const {
;     ...
; #pragma unroll
;         for (int ai = 0; ai < 2; ++ai)
; #pragma unroll
;             for (int m = 0; m < 4; ++m) { const int row = row0 + ai * HALF + m * 16; const float r = __builtin_amdgcn_rsqf(rr[ai][m] * (1.0f / D) + RMS_EPS);
;                 f4 o0, o1;
; #pragma unroll
;                 for (int e = 0; e < 4; ++e) { const float a0 = acc[ai][0][m][0][e] * r, a1 = acc[ai][0][m][1][e] * r;
;                     o0[e] = a0 * sigmoidf_(a0) * (acc[ai][1][m][0][e] * r); o1[e] = a1 * sigmoidf_(a1) * (acc[ai][1][m][1][e] * r); }
;                 *(v4u*)(uout + (size_t)row * DFF + col0) = pack8(o0, o1); }
	v_fmamk_f32 v166, v227, 0x39800000, v154
	v_rsq_f32_e32 v167, v166
	v_pk_mul_f32 v[72:73], v[76:77], v[72:73]
	v_pk_mul_f32 v[74:75], v[78:79], v[74:75]
	v_pk_mul_f32 v[64:65], v[68:69], v[64:65]
	v_pk_mul_f32 v[66:67], v[70:71], v[66:67]
	v_mul_f32_e32 v168, 0xbfb8aa3b, v167
	v_add_u32_e32 v149, 0x30, v148
	v_pk_mul_f32 v[76:77], v[76:77], v[168:169] op_sel_hi:[1,0]
	v_pk_mul_f32 v[78:79], v[78:79], v[168:169] op_sel_hi:[1,0]
	v_pk_mul_f32 v[68:69], v[68:69], v[168:169] op_sel_hi:[1,0]
	v_pk_mul_f32 v[70:71], v[70:71], v[168:169] op_sel_hi:[1,0]
	v_exp_f32_e32 v76, v76
	v_exp_f32_e32 v77, v77
	v_exp_f32_e32 v78, v78
	v_exp_f32_e32 v79, v79
	v_exp_f32_e32 v68, v68
	v_exp_f32_e32 v69, v69
	v_exp_f32_e32 v70, v70
	v_exp_f32_e32 v71, v71
	v_mad_i64_i32 v[170:171], s[0:1], v149, s52, v[164:165]
	v_pk_fma_f32 v[76:77], v[76:77], v[166:167], v[166:167] op_sel_hi:[1,0,0]
	v_pk_fma_f32 v[78:79], v[78:79], v[166:167], v[166:167] op_sel_hi:[1,0,0]
	v_pk_fma_f32 v[68:69], v[68:69], v[166:167], v[166:167] op_sel_hi:[1,0,0]
	v_pk_fma_f32 v[70:71], v[70:71], v[166:167], v[166:167] op_sel_hi:[1,0,0]
	v_rcp_f32_e32 v76, v76
	v_rcp_f32_e32 v77, v77
	v_rcp_f32_e32 v78, v78
	v_rcp_f32_e32 v79, v79
	v_rcp_f32_e32 v68, v68
	v_rcp_f32_e32 v69, v69
	v_rcp_f32_e32 v70, v70
	v_rcp_f32_e32 v71, v71
	s_nop 0
	v_pk_mul_f32 v[72:73], v[72:73], v[76:77]
	v_pk_mul_f32 v[74:75], v[74:75], v[78:79]
	v_pk_mul_f32 v[64:65], v[64:65], v[68:69]
	v_pk_mul_f32 v[66:67], v[66:67], v[70:71]
	v_cvt_pk_bf16_f32 v76, v72, v73
	v_cvt_pk_bf16_f32 v77, v74, v75
	v_cvt_pk_bf16_f32 v78, v64, v65
	v_cvt_pk_bf16_f32 v79, v66, v67
	global_store_dwordx4 v[170:171], v[76:79], off
	v_fmamk_f32 v166, v228, 0x39800000, v154
	v_rsq_f32_e32 v167, v166
	v_pk_mul_f32 v[56:57], v[60:61], v[56:57]
	v_pk_mul_f32 v[58:59], v[62:63], v[58:59]
	v_pk_mul_f32 v[48:49], v[52:53], v[48:49]
	v_pk_mul_f32 v[50:51], v[54:55], v[50:51]
	v_mul_f32_e32 v168, 0xbfb8aa3b, v167
	v_add_u32_e32 v149, 0x80, v148
	v_pk_mul_f32 v[60:61], v[60:61], v[168:169] op_sel_hi:[1,0]
	v_pk_mul_f32 v[62:63], v[62:63], v[168:169] op_sel_hi:[1,0]
	v_pk_mul_f32 v[52:53], v[52:53], v[168:169] op_sel_hi:[1,0]
	v_pk_mul_f32 v[54:55], v[54:55], v[168:169] op_sel_hi:[1,0]
	v_exp_f32_e32 v60, v60
	v_exp_f32_e32 v61, v61
	v_exp_f32_e32 v62, v62
	v_exp_f32_e32 v63, v63
	v_exp_f32_e32 v52, v52
	v_exp_f32_e32 v53, v53
	v_exp_f32_e32 v54, v54
	v_exp_f32_e32 v55, v55
	v_mad_i64_i32 v[170:171], s[0:1], v149, s52, v[164:165]
	v_pk_fma_f32 v[60:61], v[60:61], v[166:167], v[166:167] op_sel_hi:[1,0,0]
	v_pk_fma_f32 v[62:63], v[62:63], v[166:167], v[166:167] op_sel_hi:[1,0,0]
	v_pk_fma_f32 v[52:53], v[52:53], v[166:167], v[166:167] op_sel_hi:[1,0,0]
	v_pk_fma_f32 v[54:55], v[54:55], v[166:167], v[166:167] op_sel_hi:[1,0,0]
	v_rcp_f32_e32 v60, v60
	v_rcp_f32_e32 v61, v61
	v_rcp_f32_e32 v62, v62
	v_rcp_f32_e32 v63, v63
	v_rcp_f32_e32 v52, v52
	v_rcp_f32_e32 v53, v53
	v_rcp_f32_e32 v54, v54
	v_rcp_f32_e32 v55, v55
	s_nop 0
	v_pk_mul_f32 v[56:57], v[56:57], v[60:61]
	v_pk_mul_f32 v[58:59], v[58:59], v[62:63]
	v_pk_mul_f32 v[48:49], v[48:49], v[52:53]
	v_pk_mul_f32 v[50:51], v[50:51], v[54:55]
	v_cvt_pk_bf16_f32 v60, v56, v57
	v_cvt_pk_bf16_f32 v61, v58, v59
	v_cvt_pk_bf16_f32 v62, v48, v49
	v_cvt_pk_bf16_f32 v63, v50, v51
	global_store_dwordx4 v[170:171], v[60:63], off
	v_fmamk_f32 v166, v229, 0x39800000, v154
	v_rsq_f32_e32 v167, v166
	v_pk_mul_f32 v[40:41], v[44:45], v[40:41]
	v_pk_mul_f32 v[42:43], v[46:47], v[42:43]
	v_pk_mul_f32 v[32:33], v[36:37], v[32:33]
	v_pk_mul_f32 v[34:35], v[38:39], v[34:35]
	v_mul_f32_e32 v168, 0xbfb8aa3b, v167
	v_add_u32_e32 v149, 0x90, v148
	v_pk_mul_f32 v[44:45], v[44:45], v[168:169] op_sel_hi:[1,0]
	v_pk_mul_f32 v[46:47], v[46:47], v[168:169] op_sel_hi:[1,0]
	v_pk_mul_f32 v[36:37], v[36:37], v[168:169] op_sel_hi:[1,0]
	v_pk_mul_f32 v[38:39], v[38:39], v[168:169] op_sel_hi:[1,0]
	v_exp_f32_e32 v44, v44
	v_exp_f32_e32 v45, v45
	v_exp_f32_e32 v46, v46
	v_exp_f32_e32 v47, v47
	v_exp_f32_e32 v36, v36
	v_exp_f32_e32 v37, v37
	v_exp_f32_e32 v38, v38
	v_exp_f32_e32 v39, v39
	v_mad_i64_i32 v[170:171], s[0:1], v149, s52, v[164:165]
	v_pk_fma_f32 v[44:45], v[44:45], v[166:167], v[166:167] op_sel_hi:[1,0,0]
; DI float sigmoidf_(float z) { return 1.0f / (1.0f + __expf(-z)); }
; DI v4u pack8(const f4& a, const f4& b) { v4u w; w.x = cvt_pk_bf16(a[0], a[1]); w.y = cvt_pk_bf16(a[2], a[3]); w.z = cvt_pk_bf16(b[0], b[1]); w.w = cvt_pk_bf16(b[2], b[3]); return w; }
; template <class Epi, class Sched, bool ALIGN_EPI = false, bool SP2 = false>
; __device__ __forceinline__ void gemm_phase(PG8_LAS unsigned char* lds, const Gemm g, const Sched& S, const Epi& E, const int wid) {
;     ...
;         if (!has_next) break;
;         if (!Epi::CHAIN || !E.keep(cur)) {
; #pragma unroll
;         for (int a = 0; a < 2; ++a)
; #pragma unroll
;             for (int b = 0; b < 2; ++b)
; #pragma unroll
;                 for (int m = 0; m < 4; ++m)
; #pragma unroll
;                     for (int n = 0; n < 2; ++n) acc[a][b][m][n] = (f32x4){0.f, 0.f, 0.f, 0.f};
;         }
;         cur = nxt; cA = nA; cB = nB; ++ui;
;     DI void operator()(f4 (&acc)[2][2][4][2], const Unit& u, int wr, int wc, int fr, int fq) const {
;     ...
; #pragma unroll
;         for (int ai = 0; ai < 2; ++ai)
; #pragma unroll
;             for (int m = 0; m < 4; ++m) { const int row = row0 + ai * HALF + m * 16; const float r = __builtin_amdgcn_rsqf(rr[ai][m] * (1.0f / D) + RMS_EPS);
;                 f4 o0, o1;
; #pragma unroll
;                 for (int e = 0; e < 4; ++e) { const float a0 = acc[ai][0][m][0][e] * r, a1 = acc[ai][0][m][1][e] * r;
;                     o0[e] = a0 * sigmoidf_(a0) * (acc[ai][1][m][0][e] * r); o1[e] = a1 * sigmoidf_(a1) * (acc[ai][1][m][1][e] * r); }
;                 *(v4u*)(uout + (size_t)row * DFF + col0) = pack8(o0, o1); }
	v_pk_fma_f32 v[46:47], v[46:47], v[166:167], v[166:167] op_sel_hi:[1,0,0]
	v_pk_fma_f32 v[36:37], v[36:37], v[166:167], v[166:167] op_sel_hi:[1,0,0]
	v_pk_fma_f32 v[38:39], v[38:39], v[166:167], v[166:167] op_sel_hi:[1,0,0]
	v_rcp_f32_e32 v44, v44
	v_rcp_f32_e32 v45, v45
	v_rcp_f32_e32 v46, v46
	v_rcp_f32_e32 v47, v47
	v_rcp_f32_e32 v36, v36
	v_rcp_f32_e32 v37, v37
	v_rcp_f32_e32 v38, v38
	v_rcp_f32_e32 v39, v39
	s_nop 0
	v_pk_mul_f32 v[40:41], v[40:41], v[44:45]
	v_pk_mul_f32 v[42:43], v[42:43], v[46:47]
	v_pk_mul_f32 v[32:33], v[32:33], v[36:37]
	v_pk_mul_f32 v[34:35], v[34:35], v[38:39]
	v_cvt_pk_bf16_f32 v44, v40, v41
	v_cvt_pk_bf16_f32 v45, v42, v43
	v_cvt_pk_bf16_f32 v46, v32, v33
	v_cvt_pk_bf16_f32 v47, v34, v35
	global_store_dwordx4 v[170:171], v[44:47], off
	v_fmamk_f32 v166, v230, 0x39800000, v154
	v_rsq_f32_e32 v167, v166
	v_pk_mul_f32 v[24:25], v[28:29], v[24:25]
	v_pk_mul_f32 v[26:27], v[30:31], v[26:27]
	v_pk_mul_f32 v[16:17], v[20:21], v[16:17]
	v_pk_mul_f32 v[18:19], v[22:23], v[18:19]
	v_mul_f32_e32 v168, 0xbfb8aa3b, v167
	v_add_u32_e32 v149, 0xa0, v148
	v_pk_mul_f32 v[28:29], v[28:29], v[168:169] op_sel_hi:[1,0]
	v_pk_mul_f32 v[30:31], v[30:31], v[168:169] op_sel_hi:[1,0]
	v_pk_mul_f32 v[20:21], v[20:21], v[168:169] op_sel_hi:[1,0]
	v_pk_mul_f32 v[22:23], v[22:23], v[168:169] op_sel_hi:[1,0]
	v_exp_f32_e32 v28, v28
	v_exp_f32_e32 v29, v29
	v_exp_f32_e32 v30, v30
	v_exp_f32_e32 v31, v31
	v_exp_f32_e32 v20, v20
	v_exp_f32_e32 v21, v21
	v_exp_f32_e32 v22, v22
	v_exp_f32_e32 v23, v23
	v_mad_i64_i32 v[170:171], s[0:1], v149, s52, v[164:165]
	v_pk_fma_f32 v[28:29], v[28:29], v[166:167], v[166:167] op_sel_hi:[1,0,0]
	v_pk_fma_f32 v[30:31], v[30:31], v[166:167], v[166:167] op_sel_hi:[1,0,0]
	v_pk_fma_f32 v[20:21], v[20:21], v[166:167], v[166:167] op_sel_hi:[1,0,0]
	v_pk_fma_f32 v[22:23], v[22:23], v[166:167], v[166:167] op_sel_hi:[1,0,0]
	v_rcp_f32_e32 v28, v28
	v_rcp_f32_e32 v29, v29
	v_rcp_f32_e32 v30, v30
	v_rcp_f32_e32 v31, v31
	v_rcp_f32_e32 v20, v20
	v_rcp_f32_e32 v21, v21
	v_rcp_f32_e32 v22, v22
	v_rcp_f32_e32 v23, v23
	s_nop 0
	v_pk_mul_f32 v[24:25], v[24:25], v[28:29]
	v_pk_mul_f32 v[26:27], v[26:27], v[30:31]
	v_pk_mul_f32 v[16:17], v[16:17], v[20:21]
	v_pk_mul_f32 v[18:19], v[18:19], v[22:23]
	v_cvt_pk_bf16_f32 v28, v24, v25
	v_cvt_pk_bf16_f32 v29, v26, v27
	v_cvt_pk_bf16_f32 v30, v16, v17
	v_cvt_pk_bf16_f32 v31, v18, v19
	global_store_dwordx4 v[170:171], v[28:31], off
	v_fmamk_f32 v166, v231, 0x39800000, v154
	v_rsq_f32_e32 v167, v166
	v_pk_mul_f32 v[8:9], v[12:13], v[8:9]
	v_pk_mul_f32 v[10:11], v[14:15], v[10:11]
	v_pk_mul_f32 v[0:1], v[4:5], v[0:1]
	v_pk_mul_f32 v[2:3], v[6:7], v[2:3]
	v_mul_f32_e32 v168, 0xbfb8aa3b, v167
	v_add_u32_e32 v149, 0xb0, v148
	v_pk_mul_f32 v[12:13], v[12:13], v[168:169] op_sel_hi:[1,0]
	v_pk_mul_f32 v[14:15], v[14:15], v[168:169] op_sel_hi:[1,0]
	v_pk_mul_f32 v[4:5], v[4:5], v[168:169] op_sel_hi:[1,0]
	v_pk_mul_f32 v[6:7], v[6:7], v[168:169] op_sel_hi:[1,0]
	v_exp_f32_e32 v12, v12
	v_exp_f32_e32 v13, v13
	v_exp_f32_e32 v14, v14
	v_exp_f32_e32 v15, v15
	v_exp_f32_e32 v4, v4
	v_exp_f32_e32 v5, v5
	v_exp_f32_e32 v6, v6
	v_exp_f32_e32 v7, v7
	v_mad_i64_i32 v[170:171], s[0:1], v149, s52, v[164:165]
	v_pk_fma_f32 v[12:13], v[12:13], v[166:167], v[166:167] op_sel_hi:[1,0,0]
	v_pk_fma_f32 v[14:15], v[14:15], v[166:167], v[166:167] op_sel_hi:[1,0,0]
	v_pk_fma_f32 v[4:5], v[4:5], v[166:167], v[166:167] op_sel_hi:[1,0,0]
	v_pk_fma_f32 v[6:7], v[6:7], v[166:167], v[166:167] op_sel_hi:[1,0,0]
	v_rcp_f32_e32 v12, v12
	v_rcp_f32_e32 v13, v13
	v_rcp_f32_e32 v14, v14
	v_rcp_f32_e32 v15, v15
	v_rcp_f32_e32 v4, v4
	v_rcp_f32_e32 v5, v5
	v_rcp_f32_e32 v6, v6
	v_rcp_f32_e32 v7, v7
	s_nop 0
	v_pk_mul_f32 v[8:9], v[8:9], v[12:13]
	v_pk_mul_f32 v[10:11], v[10:11], v[14:15]
	v_pk_mul_f32 v[0:1], v[0:1], v[4:5]
	v_pk_mul_f32 v[2:3], v[2:3], v[6:7]
	s_andn2_b64 vcc, exec, s[4:5]
	s_mov_b64 s[0:1], -1
	v_cvt_pk_bf16_f32 v12, v8, v9
	v_cvt_pk_bf16_f32 v13, v10, v11
	v_cvt_pk_bf16_f32 v14, v0, v1
	v_cvt_pk_bf16_f32 v15, v2, v3
	global_store_dwordx4 v[170:171], v[12:15], off
	s_cbranch_vccnz .LBB0_2802
	s_andn2_b64 vcc, exec, s[12:13]
	s_cbranch_vccnz .LBB0_2801
	s_barrier
	s_branch .LBB0_2801

; template <class Epi, class Sched, bool ALIGN_EPI = false, bool SP2 = false>
; __device__ __forceinline__ void gemm_phase(PG8_LAS unsigned char* lds, const Gemm g, const Sched& S, const Epi& E, const int wid) {
;     ...
; #pragma unroll
;         for (int a = 0; a < 2; ++a)
; #pragma unroll
;             for (int b = 0; b < 2; ++b)
; #pragma unroll
;                 for (int m = 0; m < 4; ++m)
; #pragma unroll
;                     for (int n = 0; n < 2; ++n) acc[a][b][m][n] = (f32x4){0.f, 0.f, 0.f, 0.f};
;     DI void operator()(f4 (&acc)[2][2][4][2], const Unit& u, int wr, int wc, int fr, int fq) const {
;     ...
;         for (int ai = 0; ai < 2; ++ai)
; #pragma unroll
;             for (int m = 0; m < 4; ++m) rr[ai][m] = ss[row0 + ai * HALF + m * 16];
.LBB0_2825:
	s_ashr_i32 s23, s22, 31
	s_lshl_b64 s[24:25], s[22:23], 21
	s_add_u32 s24, s30, s24
	s_addc_u32 s25, s31, s25
	s_and_b64 s[26:27], s[4:5], exec
	s_cselect_b32 s23, s25, s3
	s_cselect_b32 s54, s24, s2
	s_ashr_i32 s21, s20, 31
	s_lshl_b64 s[26:27], s[20:21], 21
	s_add_u32 s26, s34, s26
	s_addc_u32 s27, s35, s27
	s_and_b64 s[28:29], s[4:5], exec
	s_cselect_b32 s21, s27, s7
	s_cselect_b32 s55, s26, s6
	s_add_u32 s2, s2, 0x100080
	s_addc_u32 s3, s3, 0
	s_add_u32 s56, s6, 0x100
	v_mov_b32_e32 v0, 0
	s_addc_u32 s57, s7, 0
	s_mov_b32 s58, -2
	v_mov_b32_e32 v1, v0
	v_mov_b32_e32 v2, v0
	v_mov_b32_e32 v3, v0
	v_mov_b32_e32 v8, v0
	v_mov_b32_e32 v9, v0
	v_mov_b32_e32 v10, v0
	v_mov_b32_e32 v11, v0
	v_mov_b32_e32 v16, v0
	v_mov_b32_e32 v17, v0
	v_mov_b32_e32 v18, v0
	v_mov_b32_e32 v19, v0
	v_mov_b32_e32 v24, v0
	v_mov_b32_e32 v25, v0
	v_mov_b32_e32 v26, v0
	v_mov_b32_e32 v27, v0
	v_mov_b32_e32 v32, v0
	v_mov_b32_e32 v33, v0
	v_mov_b32_e32 v34, v0
	v_mov_b32_e32 v35, v0
	v_mov_b32_e32 v40, v0
	v_mov_b32_e32 v41, v0
	v_mov_b32_e32 v42, v0
	v_mov_b32_e32 v43, v0
	v_mov_b32_e32 v48, v0
	v_mov_b32_e32 v49, v0
	v_mov_b32_e32 v50, v0
	v_mov_b32_e32 v51, v0
	v_mov_b32_e32 v56, v0
	v_mov_b32_e32 v57, v0
	v_mov_b32_e32 v58, v0
	v_mov_b32_e32 v59, v0
	v_mov_b32_e32 v4, v0
	v_mov_b32_e32 v5, v0
	v_mov_b32_e32 v6, v0
	v_mov_b32_e32 v7, v0
	v_mov_b32_e32 v12, v0
	v_mov_b32_e32 v13, v0
	v_mov_b32_e32 v14, v0
	v_mov_b32_e32 v15, v0
	v_mov_b32_e32 v20, v0
	v_mov_b32_e32 v21, v0
	v_mov_b32_e32 v22, v0
	v_mov_b32_e32 v23, v0
	v_mov_b32_e32 v28, v0
	v_mov_b32_e32 v29, v0
	v_mov_b32_e32 v30, v0
	v_mov_b32_e32 v31, v0
	v_mov_b32_e32 v36, v0
	v_mov_b32_e32 v37, v0
	v_mov_b32_e32 v38, v0
	v_mov_b32_e32 v39, v0
	v_mov_b32_e32 v44, v0
	v_mov_b32_e32 v45, v0
	v_mov_b32_e32 v46, v0
	v_mov_b32_e32 v47, v0
	v_mov_b32_e32 v52, v0
	v_mov_b32_e32 v53, v0
	v_mov_b32_e32 v54, v0
	v_mov_b32_e32 v55, v0
	v_mov_b32_e32 v60, v0
	v_mov_b32_e32 v61, v0
	v_mov_b32_e32 v62, v0
	v_mov_b32_e32 v63, v0
	v_mov_b32_e32 v64, v0
	v_mov_b32_e32 v65, v0
	v_mov_b32_e32 v66, v0
	v_mov_b32_e32 v67, v0
	v_mov_b32_e32 v72, v0
	v_mov_b32_e32 v73, v0
	v_mov_b32_e32 v74, v0
	v_mov_b32_e32 v75, v0
	v_mov_b32_e32 v80, v0
	v_mov_b32_e32 v81, v0
	v_mov_b32_e32 v82, v0
	v_mov_b32_e32 v83, v0
	v_mov_b32_e32 v88, v0
	v_mov_b32_e32 v89, v0
	v_mov_b32_e32 v90, v0
	v_mov_b32_e32 v91, v0
	v_mov_b32_e32 v96, v0
	v_mov_b32_e32 v97, v0
	v_mov_b32_e32 v98, v0
	v_mov_b32_e32 v99, v0
	v_mov_b32_e32 v104, v0
	v_mov_b32_e32 v105, v0
	v_mov_b32_e32 v106, v0
	v_mov_b32_e32 v107, v0
	v_mov_b32_e32 v112, v0
	v_mov_b32_e32 v113, v0
	v_mov_b32_e32 v114, v0
	v_mov_b32_e32 v115, v0
	v_mov_b32_e32 v120, v0
	v_mov_b32_e32 v121, v0
	v_mov_b32_e32 v122, v0
	v_mov_b32_e32 v123, v0
	v_mov_b32_e32 v68, v0
	v_mov_b32_e32 v69, v0
	v_mov_b32_e32 v70, v0
	v_mov_b32_e32 v71, v0
	v_mov_b32_e32 v76, v0
	v_mov_b32_e32 v77, v0
	v_mov_b32_e32 v78, v0
	v_mov_b32_e32 v79, v0
	v_mov_b32_e32 v84, v0
	v_mov_b32_e32 v85, v0
	v_mov_b32_e32 v86, v0
	v_mov_b32_e32 v87, v0
	v_mov_b32_e32 v92, v0
	v_mov_b32_e32 v93, v0
	v_mov_b32_e32 v94, v0
	v_mov_b32_e32 v95, v0
	v_mov_b32_e32 v100, v0
	v_mov_b32_e32 v101, v0
	v_mov_b32_e32 v102, v0
	v_mov_b32_e32 v103, v0
	v_mov_b32_e32 v108, v0
	v_mov_b32_e32 v109, v0
	v_mov_b32_e32 v110, v0
	v_mov_b32_e32 v111, v0
	v_mov_b32_e32 v116, v0
	v_mov_b32_e32 v117, v0
	v_mov_b32_e32 v118, v0
	v_mov_b32_e32 v119, v0
	v_mov_b32_e32 v124, v0
	v_mov_b32_e32 v125, v0
	v_mov_b32_e32 v126, v0
	v_mov_b32_e32 v127, v0
	s_lshl_b32 s98, s0, 8
	s_add_i32 s98, s98, s36
	v_mbcnt_lo_u32_b32 v232, -1, 0
	v_mbcnt_hi_u32_b32 v232, -1, v232
	v_and_or_b32 v232, v232, 15, s98
	v_ashrrev_i32_e32 v233, 31, v232
	v_lshl_add_u64 v[232:233], v[232:233], 2, s[10:11]
	global_load_dword v224, v[232:233], off
	global_load_dword v225, v[232:233], off offset:64
	global_load_dword v226, v[232:233], off offset:128
	global_load_dword v227, v[232:233], off offset:192
	global_load_dword v228, v[232:233], off offset:512
	global_load_dword v229, v[232:233], off offset:576
	global_load_dword v230, v[232:233], off offset:640
	global_load_dword v231, v[232:233], off offset:704

; DI float sigmoidf_(float z) { return 1.0f / (1.0f + __expf(-z)); }
; DI v4u pack8(const f4& a, const f4& b) { v4u w; w.x = cvt_pk_bf16(a[0], a[1]); w.y = cvt_pk_bf16(a[2], a[3]); w.z = cvt_pk_bf16(b[0], b[1]); w.w = cvt_pk_bf16(b[2], b[3]); return w; }
;     DI void operator()(f4 (&acc)[2][2][4][2], const Unit& u, int wr, int wc, int fr, int fq) const {
;     ...
; #pragma unroll
;         for (int ai = 0; ai < 2; ++ai)
; #pragma unroll
;             for (int m = 0; m < 4; ++m) { const int row = row0 + ai * HALF + m * 16; const float r = __builtin_amdgcn_rsqf(rr[ai][m] * (1.0f / D) + RMS_EPS);
;                 f4 o0, o1;
; #pragma unroll
;                 for (int e = 0; e < 4; ++e) { const float a0 = acc[ai][0][m][0][e] * r, a1 = acc[ai][0][m][1][e] * r;
;                     o0[e] = a0 * sigmoidf_(a0) * (acc[ai][1][m][0][e] * r); o1[e] = a1 * sigmoidf_(a1) * (acc[ai][1][m][1][e] * r); }
;                 *(v4u*)(uout + (size_t)row * DFF + col0) = pack8(o0, o1); }
.LBB0_2829:
	s_lshl_b32 s0, s0, 8
	s_add_i32 s0, s0, s36
	v_mbcnt_lo_u32_b32 v144, -1, 0
	v_mbcnt_hi_u32_b32 v144, -1, v144
	v_and_or_b32 v148, v144, 15, s0
	v_ashrrev_i32_e32 v149, 31, v148
	s_lshl_b32 s0, s1, 7
	s_or_b32 s0, s0, s37
	v_ashrrev_i32_e32 v145, 1, v144
	v_and_b32_e32 v145, -8, v145
	v_add_u32_e32 v164, s0, v145
	v_ashrrev_i32_e32 v165, 31, v164
	v_lshlrev_b64 v[164:165], 1, v[164:165]
	v_lshl_add_u64 v[164:165], v[164:165], 0, s[14:15]
	v_fmamk_f32 v166, v224, 0x39800000, v154
	v_rsq_f32_e32 v167, v166
	v_pk_mul_f32 v[120:121], v[124:125], v[120:121]
	v_pk_mul_f32 v[122:123], v[126:127], v[122:123]
	v_pk_mul_f32 v[112:113], v[116:117], v[112:113]
	v_pk_mul_f32 v[114:115], v[118:119], v[114:115]
	v_mul_f32_e32 v168, 0xbfb8aa3b, v167
	v_mov_b32_e32 v149, v148
	v_pk_mul_f32 v[124:125], v[124:125], v[168:169] op_sel_hi:[1,0]
	v_pk_mul_f32 v[126:127], v[126:127], v[168:169] op_sel_hi:[1,0]
	v_pk_mul_f32 v[116:117], v[116:117], v[168:169] op_sel_hi:[1,0]
	v_pk_mul_f32 v[118:119], v[118:119], v[168:169] op_sel_hi:[1,0]
	v_exp_f32_e32 v124, v124
	v_exp_f32_e32 v125, v125
	v_exp_f32_e32 v126, v126
	v_exp_f32_e32 v127, v127
	v_exp_f32_e32 v116, v116
	v_exp_f32_e32 v117, v117
	v_exp_f32_e32 v118, v118
	v_exp_f32_e32 v119, v119
	v_mad_i64_i32 v[170:171], s[0:1], v149, s53, v[164:165]
	v_pk_fma_f32 v[124:125], v[124:125], v[166:167], v[166:167] op_sel_hi:[1,0,0]
	v_pk_fma_f32 v[126:127], v[126:127], v[166:167], v[166:167] op_sel_hi:[1,0,0]
	v_pk_fma_f32 v[116:117], v[116:117], v[166:167], v[166:167] op_sel_hi:[1,0,0]
	v_pk_fma_f32 v[118:119], v[118:119], v[166:167], v[166:167] op_sel_hi:[1,0,0]
	v_rcp_f32_e32 v124, v124
	v_rcp_f32_e32 v125, v125
	v_rcp_f32_e32 v126, v126
	v_rcp_f32_e32 v127, v127
	v_rcp_f32_e32 v116, v116
	v_rcp_f32_e32 v117, v117
	v_rcp_f32_e32 v118, v118
	v_rcp_f32_e32 v119, v119
	s_nop 0
	v_pk_mul_f32 v[120:121], v[120:121], v[124:125]
	v_pk_mul_f32 v[122:123], v[122:123], v[126:127]
	v_pk_mul_f32 v[112:113], v[112:113], v[116:117]
	v_pk_mul_f32 v[114:115], v[114:115], v[118:119]
	v_cvt_pk_bf16_f32 v124, v120, v121
	v_cvt_pk_bf16_f32 v125, v122, v123
	v_cvt_pk_bf16_f32 v126, v112, v113
	v_cvt_pk_bf16_f32 v127, v114, v115
	global_store_dwordx4 v[170:171], v[124:127], off
	v_fmamk_f32 v166, v225, 0x39800000, v154
	v_rsq_f32_e32 v167, v166
	v_pk_mul_f32 v[104:105], v[108:109], v[104:105]
	v_pk_mul_f32 v[106:107], v[110:111], v[106:107]
	v_pk_mul_f32 v[96:97], v[100:101], v[96:97]
	v_pk_mul_f32 v[98:99], v[102:103], v[98:99]
	v_mul_f32_e32 v168, 0xbfb8aa3b, v167
	v_add_u32_e32 v149, 0x10, v148
	v_pk_mul_f32 v[108:109], v[108:109], v[168:169] op_sel_hi:[1,0]
	v_pk_mul_f32 v[110:111], v[110:111], v[168:169] op_sel_hi:[1,0]
	v_pk_mul_f32 v[100:101], v[100:101], v[168:169] op_sel_hi:[1,0]
	v_pk_mul_f32 v[102:103], v[102:103], v[168:169] op_sel_hi:[1,0]
	v_exp_f32_e32 v108, v108
	v_exp_f32_e32 v109, v109
	v_exp_f32_e32 v110, v110
	v_exp_f32_e32 v111, v111
	v_exp_f32_e32 v100, v100
	v_exp_f32_e32 v101, v101
	v_exp_f32_e32 v102, v102
	v_exp_f32_e32 v103, v103
	v_mad_i64_i32 v[170:171], s[0:1], v149, s53, v[164:165]
	v_pk_fma_f32 v[108:109], v[108:109], v[166:167], v[166:167] op_sel_hi:[1,0,0]
	v_pk_fma_f32 v[110:111], v[110:111], v[166:167], v[166:167] op_sel_hi:[1,0,0]
	v_pk_fma_f32 v[100:101], v[100:101], v[166:167], v[166:167] op_sel_hi:[1,0,0]
	v_pk_fma_f32 v[102:103], v[102:103], v[166:167], v[166:167] op_sel_hi:[1,0,0]
	v_rcp_f32_e32 v108, v108
	v_rcp_f32_e32 v109, v109
	v_rcp_f32_e32 v110, v110
	v_rcp_f32_e32 v111, v111
	v_rcp_f32_e32 v100, v100
	v_rcp_f32_e32 v101, v101
	v_rcp_f32_e32 v102, v102
	v_rcp_f32_e32 v103, v103
	s_nop 0
	v_pk_mul_f32 v[104:105], v[104:105], v[108:109]
	v_pk_mul_f32 v[106:107], v[106:107], v[110:111]
	v_pk_mul_f32 v[96:97], v[96:97], v[100:101]
	v_pk_mul_f32 v[98:99], v[98:99], v[102:103]
	v_cvt_pk_bf16_f32 v108, v104, v105
	v_cvt_pk_bf16_f32 v109, v106, v107
	v_cvt_pk_bf16_f32 v110, v96, v97
	v_cvt_pk_bf16_f32 v111, v98, v99
	global_store_dwordx4 v[170:171], v[108:111], off
	v_fmamk_f32 v166, v226, 0x39800000, v154
	v_rsq_f32_e32 v167, v166
	v_pk_mul_f32 v[88:89], v[92:93], v[88:89]
	v_pk_mul_f32 v[90:91], v[94:95], v[90:91]
	v_pk_mul_f32 v[80:81], v[84:85], v[80:81]
	v_pk_mul_f32 v[82:83], v[86:87], v[82:83]
	v_mul_f32_e32 v168, 0xbfb8aa3b, v167
	v_add_u32_e32 v149, 0x20, v148
	v_pk_mul_f32 v[92:93], v[92:93], v[168:169] op_sel_hi:[1,0]
	v_pk_mul_f32 v[94:95], v[94:95], v[168:169] op_sel_hi:[1,0]
	v_pk_mul_f32 v[84:85], v[84:85], v[168:169] op_sel_hi:[1,0]
	v_pk_mul_f32 v[86:87], v[86:87], v[168:169] op_sel_hi:[1,0]
	v_exp_f32_e32 v92, v92
	v_exp_f32_e32 v93, v93
	v_exp_f32_e32 v94, v94
	v_exp_f32_e32 v95, v95
	v_exp_f32_e32 v84, v84
	v_exp_f32_e32 v85, v85
	v_exp_f32_e32 v86, v86
	v_exp_f32_e32 v87, v87
	v_mad_i64_i32 v[170:171], s[0:1], v149, s53, v[164:165]
	v_pk_fma_f32 v[92:93], v[92:93], v[166:167], v[166:167] op_sel_hi:[1,0,0]
	v_pk_fma_f32 v[94:95], v[94:95], v[166:167], v[166:167] op_sel_hi:[1,0,0]
	v_pk_fma_f32 v[84:85], v[84:85], v[166:167], v[166:167] op_sel_hi:[1,0,0]
	v_pk_fma_f32 v[86:87], v[86:87], v[166:167], v[166:167] op_sel_hi:[1,0,0]
	v_rcp_f32_e32 v92, v92
	v_rcp_f32_e32 v93, v93
	v_rcp_f32_e32 v94, v94
	v_rcp_f32_e32 v95, v95
	v_rcp_f32_e32 v84, v84
	v_rcp_f32_e32 v85, v85
	v_rcp_f32_e32 v86, v86
	v_rcp_f32_e32 v87, v87
	s_nop 0
	v_pk_mul_f32 v[88:89], v[88:89], v[92:93]
	v_pk_mul_f32 v[90:91], v[90:91], v[94:95]
	v_pk_mul_f32 v[80:81], v[80:81], v[84:85]
	v_pk_mul_f32 v[82:83], v[82:83], v[86:87]
	v_cvt_pk_bf16_f32 v92, v88, v89
	v_cvt_pk_bf16_f32 v93, v90, v91
	v_cvt_pk_bf16_f32 v94, v80, v81
	v_cvt_pk_bf16_f32 v95, v82, v83
	global_store_dwordx4 v[170:171], v[92:95], off
; DI float sigmoidf_(float z) { return 1.0f / (1.0f + __expf(-z)); }
; DI v4u pack8(const f4& a, const f4& b) { v4u w; w.x = cvt_pk_bf16(a[0], a[1]); w.y = cvt_pk_bf16(a[2], a[3]); w.z = cvt_pk_bf16(b[0], b[1]); w.w = cvt_pk_bf16(b[2], b[3]); return w; }
;     DI void operator()(f4 (&acc)[2][2][4][2], const Unit& u, int wr, int wc, int fr, int fq) const {
;     ...
; #pragma unroll
;         for (int ai = 0; ai < 2; ++ai)
; #pragma unroll
;             for (int m = 0; m < 4; ++m) { const int row = row0 + ai * HALF + m * 16; const float r = __builtin_amdgcn_rsqf(rr[ai][m] * (1.0f / D) + RMS_EPS);
;                 f4 o0, o1;
; #pragma unroll
;                 for (int e = 0; e < 4; ++e) { const float a0 = acc[ai][0][m][0][e] * r, a1 = acc[ai][0][m][1][e] * r;
;                     o0[e] = a0 * sigmoidf_(a0) * (acc[ai][1][m][0][e] * r); o1[e] = a1 * sigmoidf_(a1) * (acc[ai][1][m][1][e] * r); }
;                 *(v4u*)(uout + (size_t)row * DFF + col0) = pack8(o0, o1); }
	v_fmamk_f32 v166, v227, 0x39800000, v154
	v_rsq_f32_e32 v167, v166
	v_pk_mul_f32 v[72:73], v[76:77], v[72:73]
	v_pk_mul_f32 v[74:75], v[78:79], v[74:75]
	v_pk_mul_f32 v[64:65], v[68:69], v[64:65]
	v_pk_mul_f32 v[66:67], v[70:71], v[66:67]
	v_mul_f32_e32 v168, 0xbfb8aa3b, v167
	v_add_u32_e32 v149, 0x30, v148
	v_pk_mul_f32 v[76:77], v[76:77], v[168:169] op_sel_hi:[1,0]
	v_pk_mul_f32 v[78:79], v[78:79], v[168:169] op_sel_hi:[1,0]
	v_pk_mul_f32 v[68:69], v[68:69], v[168:169] op_sel_hi:[1,0]
	v_pk_mul_f32 v[70:71], v[70:71], v[168:169] op_sel_hi:[1,0]
	v_exp_f32_e32 v76, v76
	v_exp_f32_e32 v77, v77
	v_exp_f32_e32 v78, v78
	v_exp_f32_e32 v79, v79
	v_exp_f32_e32 v68, v68
	v_exp_f32_e32 v69, v69
	v_exp_f32_e32 v70, v70
	v_exp_f32_e32 v71, v71
	v_mad_i64_i32 v[170:171], s[0:1], v149, s53, v[164:165]
	v_pk_fma_f32 v[76:77], v[76:77], v[166:167], v[166:167] op_sel_hi:[1,0,0]
	v_pk_fma_f32 v[78:79], v[78:79], v[166:167], v[166:167] op_sel_hi:[1,0,0]
	v_pk_fma_f32 v[68:69], v[68:69], v[166:167], v[166:167] op_sel_hi:[1,0,0]
	v_pk_fma_f32 v[70:71], v[70:71], v[166:167], v[166:167] op_sel_hi:[1,0,0]
	v_rcp_f32_e32 v76, v76
	v_rcp_f32_e32 v77, v77
	v_rcp_f32_e32 v78, v78
	v_rcp_f32_e32 v79, v79
	v_rcp_f32_e32 v68, v68
	v_rcp_f32_e32 v69, v69
	v_rcp_f32_e32 v70, v70
	v_rcp_f32_e32 v71, v71
	s_nop 0
	v_pk_mul_f32 v[72:73], v[72:73], v[76:77]
	v_pk_mul_f32 v[74:75], v[74:75], v[78:79]
	v_pk_mul_f32 v[64:65], v[64:65], v[68:69]
	v_pk_mul_f32 v[66:67], v[66:67], v[70:71]
	v_cvt_pk_bf16_f32 v76, v72, v73
	v_cvt_pk_bf16_f32 v77, v74, v75
	v_cvt_pk_bf16_f32 v78, v64, v65
	v_cvt_pk_bf16_f32 v79, v66, v67
	global_store_dwordx4 v[170:171], v[76:79], off
	v_fmamk_f32 v166, v228, 0x39800000, v154
	v_rsq_f32_e32 v167, v166
	v_pk_mul_f32 v[56:57], v[60:61], v[56:57]
	v_pk_mul_f32 v[58:59], v[62:63], v[58:59]
	v_pk_mul_f32 v[48:49], v[52:53], v[48:49]
	v_pk_mul_f32 v[50:51], v[54:55], v[50:51]
	v_mul_f32_e32 v168, 0xbfb8aa3b, v167
	v_add_u32_e32 v149, 0x80, v148
	v_pk_mul_f32 v[60:61], v[60:61], v[168:169] op_sel_hi:[1,0]
	v_pk_mul_f32 v[62:63], v[62:63], v[168:169] op_sel_hi:[1,0]
	v_pk_mul_f32 v[52:53], v[52:53], v[168:169] op_sel_hi:[1,0]
	v_pk_mul_f32 v[54:55], v[54:55], v[168:169] op_sel_hi:[1,0]
	v_exp_f32_e32 v60, v60
	v_exp_f32_e32 v61, v61
	v_exp_f32_e32 v62, v62
	v_exp_f32_e32 v63, v63
	v_exp_f32_e32 v52, v52
	v_exp_f32_e32 v53, v53
	v_exp_f32_e32 v54, v54
	v_exp_f32_e32 v55, v55
	v_mad_i64_i32 v[170:171], s[0:1], v149, s53, v[164:165]
	v_pk_fma_f32 v[60:61], v[60:61], v[166:167], v[166:167] op_sel_hi:[1,0,0]
	v_pk_fma_f32 v[62:63], v[62:63], v[166:167], v[166:167] op_sel_hi:[1,0,0]
	v_pk_fma_f32 v[52:53], v[52:53], v[166:167], v[166:167] op_sel_hi:[1,0,0]
	v_pk_fma_f32 v[54:55], v[54:55], v[166:167], v[166:167] op_sel_hi:[1,0,0]
	v_rcp_f32_e32 v60, v60
	v_rcp_f32_e32 v61, v61
	v_rcp_f32_e32 v62, v62
	v_rcp_f32_e32 v63, v63
	v_rcp_f32_e32 v52, v52
	v_rcp_f32_e32 v53, v53
	v_rcp_f32_e32 v54, v54
	v_rcp_f32_e32 v55, v55
	s_nop 0
	v_pk_mul_f32 v[56:57], v[56:57], v[60:61]
	v_pk_mul_f32 v[58:59], v[58:59], v[62:63]
	v_pk_mul_f32 v[48:49], v[48:49], v[52:53]
	v_pk_mul_f32 v[50:51], v[50:51], v[54:55]
	v_cvt_pk_bf16_f32 v60, v56, v57
	v_cvt_pk_bf16_f32 v61, v58, v59
	v_cvt_pk_bf16_f32 v62, v48, v49
	v_cvt_pk_bf16_f32 v63, v50, v51
	global_store_dwordx4 v[170:171], v[60:63], off
	v_fmamk_f32 v166, v229, 0x39800000, v154
	v_rsq_f32_e32 v167, v166
	v_pk_mul_f32 v[40:41], v[44:45], v[40:41]
	v_pk_mul_f32 v[42:43], v[46:47], v[42:43]
	v_pk_mul_f32 v[32:33], v[36:37], v[32:33]
	v_pk_mul_f32 v[34:35], v[38:39], v[34:35]
	v_mul_f32_e32 v168, 0xbfb8aa3b, v167
	v_add_u32_e32 v149, 0x90, v148
	v_pk_mul_f32 v[44:45], v[44:45], v[168:169] op_sel_hi:[1,0]
	v_pk_mul_f32 v[46:47], v[46:47], v[168:169] op_sel_hi:[1,0]
	v_pk_mul_f32 v[36:37], v[36:37], v[168:169] op_sel_hi:[1,0]
	v_pk_mul_f32 v[38:39], v[38:39], v[168:169] op_sel_hi:[1,0]
	v_exp_f32_e32 v44, v44
	v_exp_f32_e32 v45, v45
	v_exp_f32_e32 v46, v46
	v_exp_f32_e32 v47, v47
	v_exp_f32_e32 v36, v36
	v_exp_f32_e32 v37, v37
	v_exp_f32_e32 v38, v38
	v_exp_f32_e32 v39, v39
	v_mad_i64_i32 v[170:171], s[0:1], v149, s53, v[164:165]
	v_pk_fma_f32 v[44:45], v[44:45], v[166:167], v[166:167] op_sel_hi:[1,0,0]
; DI float sigmoidf_(float z) { return 1.0f / (1.0f + __expf(-z)); }
; DI v4u pack8(const f4& a, const f4& b) { v4u w; w.x = cvt_pk_bf16(a[0], a[1]); w.y = cvt_pk_bf16(a[2], a[3]); w.z = cvt_pk_bf16(b[0], b[1]); w.w = cvt_pk_bf16(b[2], b[3]); return w; }
; template <class Epi, class Sched, bool ALIGN_EPI = false, bool SP2 = false>
; __device__ __forceinline__ void gemm_phase(PG8_LAS unsigned char* lds, const Gemm g, const Sched& S, const Epi& E, const int wid) {
;     ...
;         if (!has_next) break;
;         if (!Epi::CHAIN || !E.keep(cur)) {
; #pragma unroll
;         for (int a = 0; a < 2; ++a)
; #pragma unroll
;             for (int b = 0; b < 2; ++b)
; #pragma unroll
;                 for (int m = 0; m < 4; ++m)
; #pragma unroll
;                     for (int n = 0; n < 2; ++n) acc[a][b][m][n] = (f32x4){0.f, 0.f, 0.f, 0.f};
;         }
;         cur = nxt; cA = nA; cB = nB; ++ui;
;     DI void operator()(f4 (&acc)[2][2][4][2], const Unit& u, int wr, int wc, int fr, int fq) const {
;     ...
; #pragma unroll
;         for (int ai = 0; ai < 2; ++ai)
; #pragma unroll
;             for (int m = 0; m < 4; ++m) { const int row = row0 + ai * HALF + m * 16; const float r = __builtin_amdgcn_rsqf(rr[ai][m] * (1.0f / D) + RMS_EPS);
;                 f4 o0, o1;
; #pragma unroll
;                 for (int e = 0; e < 4; ++e) { const float a0 = acc[ai][0][m][0][e] * r, a1 = acc[ai][0][m][1][e] * r;
;                     o0[e] = a0 * sigmoidf_(a0) * (acc[ai][1][m][0][e] * r); o1[e] = a1 * sigmoidf_(a1) * (acc[ai][1][m][1][e] * r); }
;                 *(v4u*)(uout + (size_t)row * DFF + col0) = pack8(o0, o1); }
	v_pk_fma_f32 v[46:47], v[46:47], v[166:167], v[166:167] op_sel_hi:[1,0,0]
	v_pk_fma_f32 v[36:37], v[36:37], v[166:167], v[166:167] op_sel_hi:[1,0,0]
	v_pk_fma_f32 v[38:39], v[38:39], v[166:167], v[166:167] op_sel_hi:[1,0,0]
	v_rcp_f32_e32 v44, v44
	v_rcp_f32_e32 v45, v45
	v_rcp_f32_e32 v46, v46
	v_rcp_f32_e32 v47, v47
	v_rcp_f32_e32 v36, v36
	v_rcp_f32_e32 v37, v37
	v_rcp_f32_e32 v38, v38
	v_rcp_f32_e32 v39, v39
	s_nop 0
	v_pk_mul_f32 v[40:41], v[40:41], v[44:45]
	v_pk_mul_f32 v[42:43], v[42:43], v[46:47]
	v_pk_mul_f32 v[32:33], v[32:33], v[36:37]
	v_pk_mul_f32 v[34:35], v[34:35], v[38:39]
	v_cvt_pk_bf16_f32 v44, v40, v41
	v_cvt_pk_bf16_f32 v45, v42, v43
	v_cvt_pk_bf16_f32 v46, v32, v33
	v_cvt_pk_bf16_f32 v47, v34, v35
	global_store_dwordx4 v[170:171], v[44:47], off
	v_fmamk_f32 v166, v230, 0x39800000, v154
	v_rsq_f32_e32 v167, v166
	v_pk_mul_f32 v[24:25], v[28:29], v[24:25]
	v_pk_mul_f32 v[26:27], v[30:31], v[26:27]
	v_pk_mul_f32 v[16:17], v[20:21], v[16:17]
	v_pk_mul_f32 v[18:19], v[22:23], v[18:19]
	v_mul_f32_e32 v168, 0xbfb8aa3b, v167
	v_add_u32_e32 v149, 0xa0, v148
	v_pk_mul_f32 v[28:29], v[28:29], v[168:169] op_sel_hi:[1,0]
	v_pk_mul_f32 v[30:31], v[30:31], v[168:169] op_sel_hi:[1,0]
	v_pk_mul_f32 v[20:21], v[20:21], v[168:169] op_sel_hi:[1,0]
	v_pk_mul_f32 v[22:23], v[22:23], v[168:169] op_sel_hi:[1,0]
	v_exp_f32_e32 v28, v28
	v_exp_f32_e32 v29, v29
	v_exp_f32_e32 v30, v30
	v_exp_f32_e32 v31, v31
	v_exp_f32_e32 v20, v20
	v_exp_f32_e32 v21, v21
	v_exp_f32_e32 v22, v22
	v_exp_f32_e32 v23, v23
	v_mad_i64_i32 v[170:171], s[0:1], v149, s53, v[164:165]
	v_pk_fma_f32 v[28:29], v[28:29], v[166:167], v[166:167] op_sel_hi:[1,0,0]
	v_pk_fma_f32 v[30:31], v[30:31], v[166:167], v[166:167] op_sel_hi:[1,0,0]
	v_pk_fma_f32 v[20:21], v[20:21], v[166:167], v[166:167] op_sel_hi:[1,0,0]
	v_pk_fma_f32 v[22:23], v[22:23], v[166:167], v[166:167] op_sel_hi:[1,0,0]
	v_rcp_f32_e32 v28, v28
	v_rcp_f32_e32 v29, v29
	v_rcp_f32_e32 v30, v30
	v_rcp_f32_e32 v31, v31
	v_rcp_f32_e32 v20, v20
	v_rcp_f32_e32 v21, v21
	v_rcp_f32_e32 v22, v22
	v_rcp_f32_e32 v23, v23
	s_nop 0
	v_pk_mul_f32 v[24:25], v[24:25], v[28:29]
	v_pk_mul_f32 v[26:27], v[26:27], v[30:31]
	v_pk_mul_f32 v[16:17], v[16:17], v[20:21]
	v_pk_mul_f32 v[18:19], v[18:19], v[22:23]
	v_cvt_pk_bf16_f32 v28, v24, v25
	v_cvt_pk_bf16_f32 v29, v26, v27
	v_cvt_pk_bf16_f32 v30, v16, v17
	v_cvt_pk_bf16_f32 v31, v18, v19
	global_store_dwordx4 v[170:171], v[28:31], off
	v_fmamk_f32 v166, v231, 0x39800000, v154
	v_rsq_f32_e32 v167, v166
	v_pk_mul_f32 v[8:9], v[12:13], v[8:9]
	v_pk_mul_f32 v[10:11], v[14:15], v[10:11]
	v_pk_mul_f32 v[0:1], v[4:5], v[0:1]
	v_pk_mul_f32 v[2:3], v[6:7], v[2:3]
	v_mul_f32_e32 v168, 0xbfb8aa3b, v167
	v_add_u32_e32 v149, 0xb0, v148
	v_pk_mul_f32 v[12:13], v[12:13], v[168:169] op_sel_hi:[1,0]
	v_pk_mul_f32 v[14:15], v[14:15], v[168:169] op_sel_hi:[1,0]
	v_pk_mul_f32 v[4:5], v[4:5], v[168:169] op_sel_hi:[1,0]
	v_pk_mul_f32 v[6:7], v[6:7], v[168:169] op_sel_hi:[1,0]
	v_exp_f32_e32 v12, v12
	v_exp_f32_e32 v13, v13
	v_exp_f32_e32 v14, v14
	v_exp_f32_e32 v15, v15
	v_exp_f32_e32 v4, v4
	v_exp_f32_e32 v5, v5
	v_exp_f32_e32 v6, v6
	v_exp_f32_e32 v7, v7
	v_mad_i64_i32 v[170:171], s[0:1], v149, s53, v[164:165]
	v_pk_fma_f32 v[12:13], v[12:13], v[166:167], v[166:167] op_sel_hi:[1,0,0]
	v_pk_fma_f32 v[14:15], v[14:15], v[166:167], v[166:167] op_sel_hi:[1,0,0]
	v_pk_fma_f32 v[4:5], v[4:5], v[166:167], v[166:167] op_sel_hi:[1,0,0]
	v_pk_fma_f32 v[6:7], v[6:7], v[166:167], v[166:167] op_sel_hi:[1,0,0]
	v_rcp_f32_e32 v12, v12
	v_rcp_f32_e32 v13, v13
	v_rcp_f32_e32 v14, v14
	v_rcp_f32_e32 v15, v15
	v_rcp_f32_e32 v4, v4
	v_rcp_f32_e32 v5, v5
	v_rcp_f32_e32 v6, v6
	v_rcp_f32_e32 v7, v7
	s_nop 0
	v_pk_mul_f32 v[8:9], v[8:9], v[12:13]
	v_pk_mul_f32 v[10:11], v[10:11], v[14:15]
	v_pk_mul_f32 v[0:1], v[0:1], v[4:5]
	v_pk_mul_f32 v[2:3], v[2:3], v[6:7]
	s_andn2_b64 vcc, exec, s[4:5]
	s_mov_b64 s[0:1], -1
	v_cvt_pk_bf16_f32 v12, v8, v9
	v_cvt_pk_bf16_f32 v13, v10, v11
	v_cvt_pk_bf16_f32 v14, v0, v1
	v_cvt_pk_bf16_f32 v15, v2, v3
	global_store_dwordx4 v[170:171], v[12:15], off
	s_cbranch_vccnz .LBB0_2822
	s_andn2_b64 vcc, exec, s[12:13]
	s_cbranch_vccnz .LBB0_2821
	s_barrier
	s_branch .LBB0_2821
